# mixer_pre DeltaNet conv stage: two tokens per step with packed f32 ops (same ops and association per token), eight LDS reads per trip issued together, the two tokens' norm reductions interleaved
# baseline (speedup 1.0000x reference)
; __device__ __forceinline__ float bf2f(unsigned short b) { return __uint_as_float(((unsigned)b) << 16); }
; __device__ __forceinline__ unsigned short f2bf(float f) { return (unsigned short)(pg8::cvt_pk_bf16(f, 0.f) & 0xffffu); }
; __device__ __forceinline__ float siluf_(float x) { return x * __builtin_amdgcn_rcpf(1.0f + __expf(-x)); }
; #define DPP_ADD(v, ctrl) do { const int _t = __builtin_amdgcn_update_dpp(0, __builtin_bit_cast(int, (v)), (ctrl), 0xf, 0xf, true); (v) += __builtin_bit_cast(float, _t); } while (0)
; __device__ __forceinline__ float wave_sum(float v) {
;     DPP_ADD(v, 0xB1); DPP_ADD(v, 0x4E); DPP_ADD(v, 0x141); DPP_ADD(v, 0x140);
;     const int vi = __builtin_bit_cast(int, v);
;     const float r0 = __builtin_bit_cast(float, __builtin_amdgcn_readlane(vi, 0)), r1 = __builtin_bit_cast(float, __builtin_amdgcn_readlane(vi, 16)), r2 = __builtin_bit_cast(float, __builtin_amdgcn_readlane(vi, 32)), r3 = __builtin_bit_cast(float, __builtin_amdgcn_readlane(vi, 48));
;     return (r0 + r1) + (r2 + r3);
; __device__ __forceinline__ void mixer_pre_item(int item, const float* const* in, int l, unsigned char* ws, LAS unsigned char* lds, int tid, int lane, int wave) {
;     ...
;         float xm3 = bf2f(STGD[t0 * 768 + cc]), xm2 = bf2f(STGD[(t0 + 1) * 768 + cc]), xm1 = bf2f(STGD[(t0 + 2) * 768 + cc]);
;         const float qs = (kind == 0) ? 0.125f : 1.0f;
; #pragma unroll 8
;         for (int t = 0; t < 16; ++t) { const float xc = bf2f(STGD[(t0 + t + 3) * 768 + cc]); float y = siluf_(w0 * xm3 + w1 * xm2 + w2 * xm1 + w3 * xc);
;             if (kind < 2) { const float ss = wave_sum(y * y); y *= qs * __builtin_amdgcn_rsqf(ss + EPS); }
;             dst[(size_t)t * 256] = f2bf(y);
.LBB0_615:
	s_bfe_u32 s38, s33, 0x10004
	s_lshl_b32 s43, s34, 1
	s_mul_i32 s39, s38, 0x6000
	s_and_b32 s40, s43, 0xffffff80
	s_add_i32 s44, s39, s40
	s_lshl_b32 s38, s38, 4
	s_add_u32 s38, s35, s38
	s_addc_u32 s39, s42, 0
	s_lshl_b32 s40, s31, 5
	s_andn2_b32 s40, s40, 63
	v_or_b32_e32 v8, s40, v35
	v_ashrrev_i32_e32 v9, 31, v8
	v_lshl_add_u64 v[6:7], v[8:9], 2, s[10:11]
	v_add_co_u32_e32 v10, vcc, s37, v6
	s_lshl_b64 s[40:41], s[38:39], 9
	s_nop 0
	v_addc_co_u32_e32 v11, vcc, 0, v7, vcc
	v_add_co_u32_e32 v12, vcc, s77, v6
	s_lshl_b32 s38, s31, 4
	s_nop 0
	v_addc_co_u32_e32 v13, vcc, 0, v7, vcc
	global_load_dword v5, v[6:7], off
	global_load_dword v4, v[6:7], off offset:3072
	s_nop 0
	global_load_dword v6, v[10:11], off offset:2048
	global_load_dword v7, v[12:13], off offset:1024
	s_and_b32 s45, s43, 0x180
	s_and_b32 s43, s38, 16
	s_ashr_i32 s48, s31, 3
	s_cmp_eq_u32 s48, 1
	s_mov_b32 s38, 0x3200000
	s_cselect_b32 s49, s38, 0x4200000
	s_cmp_lt_u32 s31, 8
	s_cselect_b64 vcc, -1, 0
	s_and_b64 s[38:39], vcc, exec
	s_mulk_i32 s43, 0x600
	s_cselect_b32 s49, 0x2200000, s49
	s_add_i32 s38, s43, 0
	v_lshl_add_u32 v8, v8, 1, s38
	ds_read_u16 v9, v8 offset:17920
	ds_read_u16 v11, v8 offset:19456
	ds_read_u16 v8, v8 offset:20992
	s_cmp_lt_i32 s48, 2
	s_cselect_b64 s[38:39], -1, 0
	s_add_u32 s40, s49, s40
	s_addc_u32 s41, 0, s41
	s_or_b32 s40, s40, s45
	v_cndmask_b32_e32 v0, 1.0, v231, vcc
	v_add_u32_e32 v19, s44, v18
	s_mov_b32 s43, 0
	s_waitcnt lgkmcnt(2)
	v_lshlrev_b32_e32 v10, 16, v9
	s_waitcnt lgkmcnt(1)
	v_lshlrev_b32_e32 v13, 16, v11
	s_waitcnt lgkmcnt(0)
	v_lshlrev_b32_e32 v12, 16, v8
	v_lshl_add_u64 v[8:9], v[2:3], 0, s[40:41]
	s_waitcnt vmcnt(0)
	v_mov_b32_e32 v116, v10
	v_mov_b32_e32 v117, v13
	v_mov_b32_e32 v118, v13
	v_mov_b32_e32 v119, v12
	v_mov_b32_e32 v134, 0xbfb8aa3b
	v_mov_b32_e32 v136, 1.0
.Lcv_loop:
	v_add_u32_e32 v20, s43, v19
	ds_read_u16 v108, v20
	ds_read_u16 v109, v20 offset:1536
	ds_read_u16 v110, v20 offset:3072
	ds_read_u16 v111, v20 offset:4608
	ds_read_u16 v112, v20 offset:6144
	ds_read_u16 v113, v20 offset:7680
	ds_read_u16 v114, v20 offset:9216
	ds_read_u16 v115, v20 offset:10752
	s_waitcnt lgkmcnt(6)
	v_lshlrev_b32_e32 v121, 16, v108
	v_lshlrev_b32_e32 v122, 16, v108
	v_lshlrev_b32_e32 v123, 16, v109
	v_mov_b32_e32 v120, v119
	v_pk_mul_f32 v[124:125], v[116:117], v[4:5] op_sel:[0,1]
	v_pk_mul_f32 v[126:127], v[118:119], v[4:5] op_sel_hi:[1,0]
	v_pk_mul_f32 v[130:131], v[120:121], v[6:7] op_sel_hi:[1,0]
	v_pk_add_f32 v[128:129], v[124:125], v[126:127]
	v_pk_mul_f32 v[124:125], v[122:123], v[6:7] op_sel:[0,1]
	v_pk_add_f32 v[128:129], v[130:131], v[128:129]
	v_pk_add_f32 v[128:129], v[128:129], v[124:125]
	v_pk_mul_f32 v[130:131], v[128:129], v[134:135] op_sel_hi:[1,0]
	v_exp_f32_e32 v130, v130
	v_exp_f32_e32 v131, v131
	s_nop 0
	v_pk_add_f32 v[130:131], v[130:131], v[136:137] op_sel_hi:[1,0]
	v_rcp_f32_e32 v130, v130
	v_rcp_f32_e32 v131, v131
	s_nop 0
	v_pk_mul_f32 v[128:129], v[128:129], v[130:131]
	s_and_b64 vcc, exec, s[38:39]
	s_cbranch_vccz .Lcv_nn0
	v_mul_f32_e32 v138, v128, v128
	v_mul_f32_e32 v139, v129, v129
	s_nop 0
	v_mov_b32_dpp v138, v138 quad_perm:[1,0,3,2] row_mask:0xf bank_mask:0xf bound_ctrl:1
	v_mov_b32_dpp v139, v139 quad_perm:[1,0,3,2] row_mask:0xf bank_mask:0xf bound_ctrl:1
	v_fmac_f32_e32 v138, v128, v128
	v_fmac_f32_e32 v139, v129, v129
	s_nop 0
	v_add_f32_dpp v138, v138, v138 quad_perm:[2,3,0,1] row_mask:0xf bank_mask:0xf bound_ctrl:1
	v_add_f32_dpp v139, v139, v139 quad_perm:[2,3,0,1] row_mask:0xf bank_mask:0xf bound_ctrl:1
	s_nop 0
	v_add_f32_dpp v138, v138, v138 row_half_mirror row_mask:0xf bank_mask:0xf bound_ctrl:1
	v_add_f32_dpp v139, v139, v139 row_half_mirror row_mask:0xf bank_mask:0xf bound_ctrl:1
	s_nop 0
	v_add_f32_dpp v138, v138, v138 row_mirror row_mask:0xf bank_mask:0xf bound_ctrl:1
	v_add_f32_dpp v139, v139, v139 row_mirror row_mask:0xf bank_mask:0xf bound_ctrl:1
	s_nop 0
	v_readlane_b32 s48, v138, 16
	v_readlane_b32 s49, v138, 48
	v_readlane_b32 s44, v138, 0
	v_readlane_b32 s45, v138, 32
	v_readlane_b32 s100, v139, 16
	v_readlane_b32 s101, v139, 48
	v_readlane_b32 s40, v139, 0
	v_readlane_b32 s41, v139, 32
	v_mov_b32_e32 v140, s48
	v_mov_b32_e32 v141, s49
	v_mov_b32_e32 v142, s100
	v_mov_b32_e32 v143, s101
	v_pk_add_f32 v[140:141], s[44:45], v[140:141]
	v_pk_add_f32 v[142:143], s[40:41], v[142:143]
	v_add_f32_e32 v138, v140, v141
	v_add_f32_e32 v139, v142, v143
	v_add_f32_e32 v138, 0x358637bd, v138
	v_add_f32_e32 v139, 0x358637bd, v139
	v_rsq_f32_e32 v138, v138
	v_rsq_f32_e32 v139, v139
	s_nop 0
	v_mul_f32_e32 v138, v0, v138
	v_mul_f32_e32 v139, v0, v139
	v_mul_f32_e32 v128, v128, v138
	v_mul_f32_e32 v129, v129, v139
; __device__ __forceinline__ float bf2f(unsigned short b) { return __uint_as_float(((unsigned)b) << 16); }
; __device__ __forceinline__ unsigned short f2bf(float f) { return (unsigned short)(pg8::cvt_pk_bf16(f, 0.f) & 0xffffu); }
; __device__ __forceinline__ float siluf_(float x) { return x * __builtin_amdgcn_rcpf(1.0f + __expf(-x)); }
; #define DPP_ADD(v, ctrl) do { const int _t = __builtin_amdgcn_update_dpp(0, __builtin_bit_cast(int, (v)), (ctrl), 0xf, 0xf, true); (v) += __builtin_bit_cast(float, _t); } while (0)
; __device__ __forceinline__ float wave_sum(float v) {
;     DPP_ADD(v, 0xB1); DPP_ADD(v, 0x4E); DPP_ADD(v, 0x141); DPP_ADD(v, 0x140);
;     const int vi = __builtin_bit_cast(int, v);
;     const float r0 = __builtin_bit_cast(float, __builtin_amdgcn_readlane(vi, 0)), r1 = __builtin_bit_cast(float, __builtin_amdgcn_readlane(vi, 16)), r2 = __builtin_bit_cast(float, __builtin_amdgcn_readlane(vi, 32)), r3 = __builtin_bit_cast(float, __builtin_amdgcn_readlane(vi, 48));
;     return (r0 + r1) + (r2 + r3);
; }
; __device__ __forceinline__ void mixer_pre_item(int item, const float* const* in, int l, unsigned char* ws, LAS unsigned char* lds, int tid, int lane, int wave) {
;     ...
; #pragma unroll 8
;         for (int t = 0; t < 16; ++t) { const float xc = bf2f(STGD[(t0 + t + 3) * 768 + cc]); float y = siluf_(w0 * xm3 + w1 * xm2 + w2 * xm1 + w3 * xc);
;             if (kind < 2) { const float ss = wave_sum(y * y); y *= qs * __builtin_amdgcn_rsqf(ss + EPS); }
;             dst[(size_t)t * 256] = f2bf(y);
;             xm3 = xm2; xm2 = xm1; xm1 = xc; }
.Lcv_nn0:
	v_cvt_pk_bf16_f32 v126, v128, v1
	v_cvt_pk_bf16_f32 v127, v129, v1
	global_store_short v[8:9], v126, off offset:-2048
	global_store_short v[8:9], v127, off offset:-1536
	s_waitcnt lgkmcnt(4)
	v_lshlrev_b32_e32 v117, 16, v110
	v_lshlrev_b32_e32 v118, 16, v110
	v_lshlrev_b32_e32 v119, 16, v111
	v_mov_b32_e32 v116, v123
	v_pk_mul_f32 v[124:125], v[120:121], v[4:5] op_sel:[0,1]
	v_pk_mul_f32 v[126:127], v[122:123], v[4:5] op_sel_hi:[1,0]
	v_pk_mul_f32 v[130:131], v[116:117], v[6:7] op_sel_hi:[1,0]
	v_pk_add_f32 v[128:129], v[124:125], v[126:127]
	v_pk_mul_f32 v[124:125], v[118:119], v[6:7] op_sel:[0,1]
	v_pk_add_f32 v[128:129], v[130:131], v[128:129]
	v_pk_add_f32 v[128:129], v[128:129], v[124:125]
	v_pk_mul_f32 v[130:131], v[128:129], v[134:135] op_sel_hi:[1,0]
	v_exp_f32_e32 v130, v130
	v_exp_f32_e32 v131, v131
	s_nop 0
	v_pk_add_f32 v[130:131], v[130:131], v[136:137] op_sel_hi:[1,0]
	v_rcp_f32_e32 v130, v130
	v_rcp_f32_e32 v131, v131
	s_nop 0
	v_pk_mul_f32 v[128:129], v[128:129], v[130:131]
	s_and_b64 vcc, exec, s[38:39]
	s_cbranch_vccz .Lcv_nn1
	v_mul_f32_e32 v138, v128, v128
	v_mul_f32_e32 v139, v129, v129
	s_nop 0
	v_mov_b32_dpp v138, v138 quad_perm:[1,0,3,2] row_mask:0xf bank_mask:0xf bound_ctrl:1
	v_mov_b32_dpp v139, v139 quad_perm:[1,0,3,2] row_mask:0xf bank_mask:0xf bound_ctrl:1
	v_fmac_f32_e32 v138, v128, v128
	v_fmac_f32_e32 v139, v129, v129
	s_nop 0
	v_add_f32_dpp v138, v138, v138 quad_perm:[2,3,0,1] row_mask:0xf bank_mask:0xf bound_ctrl:1
	v_add_f32_dpp v139, v139, v139 quad_perm:[2,3,0,1] row_mask:0xf bank_mask:0xf bound_ctrl:1
	s_nop 0
	v_add_f32_dpp v138, v138, v138 row_half_mirror row_mask:0xf bank_mask:0xf bound_ctrl:1
	v_add_f32_dpp v139, v139, v139 row_half_mirror row_mask:0xf bank_mask:0xf bound_ctrl:1
	s_nop 0
	v_add_f32_dpp v138, v138, v138 row_mirror row_mask:0xf bank_mask:0xf bound_ctrl:1
	v_add_f32_dpp v139, v139, v139 row_mirror row_mask:0xf bank_mask:0xf bound_ctrl:1
	s_nop 0
	v_readlane_b32 s48, v138, 16
	v_readlane_b32 s49, v138, 48
	v_readlane_b32 s44, v138, 0
	v_readlane_b32 s45, v138, 32
	v_readlane_b32 s100, v139, 16
	v_readlane_b32 s101, v139, 48
	v_readlane_b32 s40, v139, 0
	v_readlane_b32 s41, v139, 32
	v_mov_b32_e32 v140, s48
	v_mov_b32_e32 v141, s49
	v_mov_b32_e32 v142, s100
	v_mov_b32_e32 v143, s101
	v_pk_add_f32 v[140:141], s[44:45], v[140:141]
	v_pk_add_f32 v[142:143], s[40:41], v[142:143]
	v_add_f32_e32 v138, v140, v141
	v_add_f32_e32 v139, v142, v143
	v_add_f32_e32 v138, 0x358637bd, v138
	v_add_f32_e32 v139, 0x358637bd, v139
	v_rsq_f32_e32 v138, v138
	v_rsq_f32_e32 v139, v139
	s_nop 0
	v_mul_f32_e32 v138, v0, v138
	v_mul_f32_e32 v139, v0, v139
	v_mul_f32_e32 v128, v128, v138
	v_mul_f32_e32 v129, v129, v139
.Lcv_nn1:
	v_cvt_pk_bf16_f32 v126, v128, v1
	v_cvt_pk_bf16_f32 v127, v129, v1
	global_store_short v[8:9], v126, off offset:-1024
	global_store_short v[8:9], v127, off offset:-512
	s_waitcnt lgkmcnt(2)
	v_lshlrev_b32_e32 v121, 16, v112
	v_lshlrev_b32_e32 v122, 16, v112
	v_lshlrev_b32_e32 v123, 16, v113
	v_mov_b32_e32 v120, v119
	v_pk_mul_f32 v[124:125], v[116:117], v[4:5] op_sel:[0,1]
	v_pk_mul_f32 v[126:127], v[118:119], v[4:5] op_sel_hi:[1,0]
	v_pk_mul_f32 v[130:131], v[120:121], v[6:7] op_sel_hi:[1,0]
	v_pk_add_f32 v[128:129], v[124:125], v[126:127]
	v_pk_mul_f32 v[124:125], v[122:123], v[6:7] op_sel:[0,1]
	v_pk_add_f32 v[128:129], v[130:131], v[128:129]
	v_pk_add_f32 v[128:129], v[128:129], v[124:125]
	v_pk_mul_f32 v[130:131], v[128:129], v[134:135] op_sel_hi:[1,0]
	v_exp_f32_e32 v130, v130
	v_exp_f32_e32 v131, v131
	s_nop 0
	v_pk_add_f32 v[130:131], v[130:131], v[136:137] op_sel_hi:[1,0]
	v_rcp_f32_e32 v130, v130
	v_rcp_f32_e32 v131, v131
	s_nop 0
	v_pk_mul_f32 v[128:129], v[128:129], v[130:131]
	s_and_b64 vcc, exec, s[38:39]
	s_cbranch_vccz .Lcv_nn2
	v_mul_f32_e32 v138, v128, v128
	v_mul_f32_e32 v139, v129, v129
	s_nop 0
	v_mov_b32_dpp v138, v138 quad_perm:[1,0,3,2] row_mask:0xf bank_mask:0xf bound_ctrl:1
	v_mov_b32_dpp v139, v139 quad_perm:[1,0,3,2] row_mask:0xf bank_mask:0xf bound_ctrl:1
	v_fmac_f32_e32 v138, v128, v128
	v_fmac_f32_e32 v139, v129, v129
	s_nop 0
	v_add_f32_dpp v138, v138, v138 quad_perm:[2,3,0,1] row_mask:0xf bank_mask:0xf bound_ctrl:1
	v_add_f32_dpp v139, v139, v139 quad_perm:[2,3,0,1] row_mask:0xf bank_mask:0xf bound_ctrl:1
	s_nop 0
	v_add_f32_dpp v138, v138, v138 row_half_mirror row_mask:0xf bank_mask:0xf bound_ctrl:1
	v_add_f32_dpp v139, v139, v139 row_half_mirror row_mask:0xf bank_mask:0xf bound_ctrl:1
	s_nop 0
	v_add_f32_dpp v138, v138, v138 row_mirror row_mask:0xf bank_mask:0xf bound_ctrl:1
	v_add_f32_dpp v139, v139, v139 row_mirror row_mask:0xf bank_mask:0xf bound_ctrl:1
	s_nop 0
	v_readlane_b32 s48, v138, 16
	v_readlane_b32 s49, v138, 48
	v_readlane_b32 s44, v138, 0
	v_readlane_b32 s45, v138, 32
	v_readlane_b32 s100, v139, 16
	v_readlane_b32 s101, v139, 48
	v_readlane_b32 s40, v139, 0
	v_readlane_b32 s41, v139, 32
	v_mov_b32_e32 v140, s48
	v_mov_b32_e32 v141, s49
	v_mov_b32_e32 v142, s100
	v_mov_b32_e32 v143, s101
	v_pk_add_f32 v[140:141], s[44:45], v[140:141]
	v_pk_add_f32 v[142:143], s[40:41], v[142:143]
	v_add_f32_e32 v138, v140, v141
	v_add_f32_e32 v139, v142, v143
	v_add_f32_e32 v138, 0x358637bd, v138
	v_add_f32_e32 v139, 0x358637bd, v139
	v_rsq_f32_e32 v138, v138
	v_rsq_f32_e32 v139, v139
	s_nop 0
	v_mul_f32_e32 v138, v0, v138
	v_mul_f32_e32 v139, v0, v139
	v_mul_f32_e32 v128, v128, v138
	v_mul_f32_e32 v129, v129, v139
; __device__ __forceinline__ float bf2f(unsigned short b) { return __uint_as_float(((unsigned)b) << 16); }
; __device__ __forceinline__ unsigned short f2bf(float f) { return (unsigned short)(pg8::cvt_pk_bf16(f, 0.f) & 0xffffu); }
; __device__ __forceinline__ float siluf_(float x) { return x * __builtin_amdgcn_rcpf(1.0f + __expf(-x)); }
; #define DPP_ADD(v, ctrl) do { const int _t = __builtin_amdgcn_update_dpp(0, __builtin_bit_cast(int, (v)), (ctrl), 0xf, 0xf, true); (v) += __builtin_bit_cast(float, _t); } while (0)
; __device__ __forceinline__ float wave_sum(float v) {
;     DPP_ADD(v, 0xB1); DPP_ADD(v, 0x4E); DPP_ADD(v, 0x141); DPP_ADD(v, 0x140);
;     const int vi = __builtin_bit_cast(int, v);
;     const float r0 = __builtin_bit_cast(float, __builtin_amdgcn_readlane(vi, 0)), r1 = __builtin_bit_cast(float, __builtin_amdgcn_readlane(vi, 16)), r2 = __builtin_bit_cast(float, __builtin_amdgcn_readlane(vi, 32)), r3 = __builtin_bit_cast(float, __builtin_amdgcn_readlane(vi, 48));
;     return (r0 + r1) + (r2 + r3);
; }
; __device__ __forceinline__ void mixer_pre_item(int item, const float* const* in, int l, unsigned char* ws, LAS unsigned char* lds, int tid, int lane, int wave) {
;     ...
; #pragma unroll 8
;         for (int t = 0; t < 16; ++t) { const float xc = bf2f(STGD[(t0 + t + 3) * 768 + cc]); float y = siluf_(w0 * xm3 + w1 * xm2 + w2 * xm1 + w3 * xc);
;             if (kind < 2) { const float ss = wave_sum(y * y); y *= qs * __builtin_amdgcn_rsqf(ss + EPS); }
;             dst[(size_t)t * 256] = f2bf(y);
;             xm3 = xm2; xm2 = xm1; xm1 = xc; }
.Lcv_nn2:
	v_cvt_pk_bf16_f32 v126, v128, v1
	v_cvt_pk_bf16_f32 v127, v129, v1
	global_store_short v[8:9], v126, off
	global_store_short v[8:9], v127, off offset:512
	s_waitcnt lgkmcnt(0)
	v_lshlrev_b32_e32 v117, 16, v114
	v_lshlrev_b32_e32 v118, 16, v114
	v_lshlrev_b32_e32 v119, 16, v115
	v_mov_b32_e32 v116, v123
	v_pk_mul_f32 v[124:125], v[120:121], v[4:5] op_sel:[0,1]
	v_pk_mul_f32 v[126:127], v[122:123], v[4:5] op_sel_hi:[1,0]
	v_pk_mul_f32 v[130:131], v[116:117], v[6:7] op_sel_hi:[1,0]
	v_pk_add_f32 v[128:129], v[124:125], v[126:127]
	v_pk_mul_f32 v[124:125], v[118:119], v[6:7] op_sel:[0,1]
	v_pk_add_f32 v[128:129], v[130:131], v[128:129]
	v_pk_add_f32 v[128:129], v[128:129], v[124:125]
	v_pk_mul_f32 v[130:131], v[128:129], v[134:135] op_sel_hi:[1,0]
	v_exp_f32_e32 v130, v130
	v_exp_f32_e32 v131, v131
	s_nop 0
	v_pk_add_f32 v[130:131], v[130:131], v[136:137] op_sel_hi:[1,0]
	v_rcp_f32_e32 v130, v130
	v_rcp_f32_e32 v131, v131
	s_nop 0
	v_pk_mul_f32 v[128:129], v[128:129], v[130:131]
	s_and_b64 vcc, exec, s[38:39]
	s_cbranch_vccz .Lcv_nn3
	v_mul_f32_e32 v138, v128, v128
	v_mul_f32_e32 v139, v129, v129
	s_nop 0
	v_mov_b32_dpp v138, v138 quad_perm:[1,0,3,2] row_mask:0xf bank_mask:0xf bound_ctrl:1
	v_mov_b32_dpp v139, v139 quad_perm:[1,0,3,2] row_mask:0xf bank_mask:0xf bound_ctrl:1
	v_fmac_f32_e32 v138, v128, v128
	v_fmac_f32_e32 v139, v129, v129
	s_nop 0
	v_add_f32_dpp v138, v138, v138 quad_perm:[2,3,0,1] row_mask:0xf bank_mask:0xf bound_ctrl:1
	v_add_f32_dpp v139, v139, v139 quad_perm:[2,3,0,1] row_mask:0xf bank_mask:0xf bound_ctrl:1
	s_nop 0
	v_add_f32_dpp v138, v138, v138 row_half_mirror row_mask:0xf bank_mask:0xf bound_ctrl:1
	v_add_f32_dpp v139, v139, v139 row_half_mirror row_mask:0xf bank_mask:0xf bound_ctrl:1
	s_nop 0
	v_add_f32_dpp v138, v138, v138 row_mirror row_mask:0xf bank_mask:0xf bound_ctrl:1
	v_add_f32_dpp v139, v139, v139 row_mirror row_mask:0xf bank_mask:0xf bound_ctrl:1
	s_nop 0
	v_readlane_b32 s48, v138, 16
	v_readlane_b32 s49, v138, 48
	v_readlane_b32 s44, v138, 0
	v_readlane_b32 s45, v138, 32
	v_readlane_b32 s100, v139, 16
	v_readlane_b32 s101, v139, 48
	v_readlane_b32 s40, v139, 0
	v_readlane_b32 s41, v139, 32
	v_mov_b32_e32 v140, s48
	v_mov_b32_e32 v141, s49
	v_mov_b32_e32 v142, s100
	v_mov_b32_e32 v143, s101
	v_pk_add_f32 v[140:141], s[44:45], v[140:141]
	v_pk_add_f32 v[142:143], s[40:41], v[142:143]
	v_add_f32_e32 v138, v140, v141
	v_add_f32_e32 v139, v142, v143
	v_add_f32_e32 v138, 0x358637bd, v138
	v_add_f32_e32 v139, 0x358637bd, v139
	v_rsq_f32_e32 v138, v138
	v_rsq_f32_e32 v139, v139
	s_nop 0
	v_mul_f32_e32 v138, v0, v138
	v_mul_f32_e32 v139, v0, v139
	v_mul_f32_e32 v128, v128, v138
	v_mul_f32_e32 v129, v129, v139
.Lcv_nn3:
	v_cvt_pk_bf16_f32 v126, v128, v1
	v_cvt_pk_bf16_f32 v127, v129, v1
	global_store_short v[8:9], v126, off offset:1024
	global_store_short v[8:9], v127, off offset:1536
	s_addk_i32 s43, 0x3000
	v_lshl_add_u64 v[8:9], v[8:9], 0, s[4:5]
	s_cmpk_eq_i32 s43, 0x6000
	s_cbranch_scc0 .Lcv_loop
	s_branch .LBB0_614
